# scan: 2 barriers per step, DMA groups {W,U,QG} and {KGT,ATT}
# speedup vs baseline: 1.0032x; 1.0032x over previous
.Lsc_step:
	ds_read_b128 v[212:215], v2
	ds_read_b128 v[216:219], v2 offset:4096
	ds_read_b128 v[220:223], v2 offset:8192
	ds_read_b128 v[224:227], v2 offset:12288
	ds_read_b128 v[228:231], v2 offset:1024
	ds_read2st64_b64 v[188:191], v131 offset0:112 offset1:113
	ds_read2st64_b64 v[192:195], v131 offset0:114 offset1:115
	v_cvt_pk_bf16_f32 v132, v16, v17
	v_cvt_pk_bf16_f32 v133, v18, v19
	v_cvt_pk_bf16_f32 v134, v4, v5
	v_cvt_pk_bf16_f32 v135, v6, v7
	v_cvt_pk_bf16_f32 v136, v44, v45
	v_cvt_pk_bf16_f32 v137, v46, v47
	v_cvt_pk_bf16_f32 v138, v76, v77
	v_cvt_pk_bf16_f32 v139, v78, v79
	v_cvt_pk_bf16_f32 v140, v84, v85
	v_cvt_pk_bf16_f32 v141, v86, v87
	v_cvt_pk_bf16_f32 v142, v88, v89
	v_cvt_pk_bf16_f32 v143, v90, v91
	v_cvt_pk_bf16_f32 v144, v92, v93
	v_cvt_pk_bf16_f32 v145, v94, v95
	v_cvt_pk_bf16_f32 v146, v96, v97
	v_cvt_pk_bf16_f32 v147, v98, v99
	v_add_u32_e32 v197, 0x4000c00, v114
	s_waitcnt lgkmcnt(6)
	v_mfma_f32_16x16x32_bf16 v[156:159], v[212:215], v[132:135], 0
	ds_read_b128 v[232:235], v2 offset:5120
	s_waitcnt lgkmcnt(6)
	v_mfma_f32_16x16x32_bf16 v[160:163], v[216:219], v[132:135], 0
	ds_read_b128 v[236:239], v2 offset:9216
	s_waitcnt lgkmcnt(6)
	v_mfma_f32_16x16x32_bf16 v[164:167], v[220:223], v[132:135], 0
	ds_read_b128 v[212:215], v2 offset:13312
	s_waitcnt lgkmcnt(6)
	v_mfma_f32_16x16x32_bf16 v[168:171], v[224:227], v[132:135], 0
	ds_read_b128 v[216:219], v2 offset:2048
	s_waitcnt lgkmcnt(6)
	v_mfma_f32_16x16x32_bf16 v[156:159], v[228:231], v[136:139], v[156:159]
	ds_read_b128 v[220:223], v2 offset:6144
	s_waitcnt lgkmcnt(4)
	v_mfma_f32_16x16x32_bf16 v[160:163], v[232:235], v[136:139], v[160:163]
	ds_read_b128 v[224:227], v2 offset:10240
	s_waitcnt lgkmcnt(4)
	v_mfma_f32_16x16x32_bf16 v[164:167], v[236:239], v[136:139], v[164:167]
	ds_read_b128 v[228:231], v2 offset:14336
	s_waitcnt lgkmcnt(4)
	v_mfma_f32_16x16x32_bf16 v[168:171], v[212:215], v[136:139], v[168:171]
	ds_read_b128 v[232:235], v2 offset:3072
	s_waitcnt lgkmcnt(4)
	v_mfma_f32_16x16x32_bf16 v[156:159], v[216:219], v[140:143], v[156:159]
	ds_read_b128 v[236:239], v2 offset:7168
	s_waitcnt lgkmcnt(4)
	v_mfma_f32_16x16x32_bf16 v[160:163], v[220:223], v[140:143], v[160:163]
	ds_read_b128 v[212:215], v2 offset:11264
	s_waitcnt lgkmcnt(4)
	v_mfma_f32_16x16x32_bf16 v[164:167], v[224:227], v[140:143], v[164:167]
	ds_read_b128 v[216:219], v2 offset:15360
	s_waitcnt lgkmcnt(4)
	v_mfma_f32_16x16x32_bf16 v[168:171], v[228:231], v[140:143], v[168:171]
	s_waitcnt lgkmcnt(3)
	v_mfma_f32_16x16x32_bf16 v[156:159], v[232:235], v[144:147], v[156:159]
	s_waitcnt lgkmcnt(2)
	v_mfma_f32_16x16x32_bf16 v[160:163], v[236:239], v[144:147], v[160:163]
	s_waitcnt lgkmcnt(1)
	v_mfma_f32_16x16x32_bf16 v[164:167], v[212:215], v[144:147], v[164:167]
	s_waitcnt lgkmcnt(0)
	v_mfma_f32_16x16x32_bf16 v[168:171], v[216:219], v[144:147], v[168:171]
	s_waitcnt lgkmcnt(0)
	ds_read_b128 v[220:223], v2 offset:16384
	ds_read_b128 v[224:227], v2 offset:20480
	ds_read_b128 v[228:231], v2 offset:24576
	ds_read_b128 v[232:235], v2 offset:28672
	ds_read_b128 v[236:239], v2 offset:17408
	s_sub_i32 s10, 0x7f, s6
	s_and_b32 s11, s10, 63
	v_readlane_b32 s96, v34, s11
	v_readlane_b32 s97, v35, s11
	s_nop 1
	s_cmp_lt_u32 s10, 64
	s_cselect_b32 s96, s96, s97
	v_mov_b32_e32 v196, s96
	s_waitcnt lgkmcnt(4)
	v_mfma_f32_16x16x32_bf16 v[172:175], v[220:223], v[132:135], 0
	ds_read_b128 v[212:215], v2 offset:21504
	v_pk_mul_f32 v[16:17], v[16:17], v[196:197] op_sel_hi:[1,0]
	v_pk_mul_f32 v[18:19], v[18:19], v[196:197] op_sel_hi:[1,0]
	s_waitcnt lgkmcnt(4)
	v_mfma_f32_16x16x32_bf16 v[176:179], v[224:227], v[132:135], 0
	ds_read_b128 v[216:219], v2 offset:25600
	v_pk_mul_f32 v[4:5], v[4:5], v[196:197] op_sel_hi:[1,0]
	v_pk_mul_f32 v[6:7], v[6:7], v[196:197] op_sel_hi:[1,0]
	s_waitcnt lgkmcnt(4)
	v_mfma_f32_16x16x32_bf16 v[180:183], v[228:231], v[132:135], 0
	ds_read_b128 v[220:223], v2 offset:29696
	v_pk_mul_f32 v[44:45], v[44:45], v[196:197] op_sel_hi:[1,0]
	v_pk_mul_f32 v[46:47], v[46:47], v[196:197] op_sel_hi:[1,0]
	v_lshlrev_b32_e32 v240, 16, v188
	v_and_b32_e32 v241, 0xffff0000, v188
	v_lshlrev_b32_e32 v242, 16, v189
	v_and_b32_e32 v243, 0xffff0000, v189
	s_waitcnt lgkmcnt(4)
	v_mfma_f32_16x16x32_bf16 v[184:187], v[232:235], v[132:135], 0
	ds_read_b128 v[224:227], v2 offset:18432
	v_pk_mul_f32 v[76:77], v[76:77], v[196:197] op_sel_hi:[1,0]
	v_pk_mul_f32 v[78:79], v[78:79], v[196:197] op_sel_hi:[1,0]
	v_sub_f32_e32 v156, v240, v156
	v_sub_f32_e32 v157, v241, v157
	v_sub_f32_e32 v158, v242, v158
	v_sub_f32_e32 v159, v243, v159
	s_waitcnt lgkmcnt(4)
	v_mfma_f32_16x16x32_bf16 v[172:175], v[236:239], v[136:139], v[172:175]
	ds_read_b128 v[228:231], v2 offset:22528
	v_pk_mul_f32 v[84:85], v[84:85], v[196:197] op_sel_hi:[1,0]
	v_pk_mul_f32 v[86:87], v[86:87], v[196:197] op_sel_hi:[1,0]
	v_lshlrev_b32_e32 v240, 16, v190
	v_and_b32_e32 v241, 0xffff0000, v190
	v_lshlrev_b32_e32 v242, 16, v191
	v_and_b32_e32 v243, 0xffff0000, v191
	s_waitcnt lgkmcnt(4)
	v_mfma_f32_16x16x32_bf16 v[176:179], v[212:215], v[136:139], v[176:179]
	ds_read_b128 v[232:235], v2 offset:26624
	v_pk_mul_f32 v[88:89], v[88:89], v[196:197] op_sel_hi:[1,0]
	v_pk_mul_f32 v[90:91], v[90:91], v[196:197] op_sel_hi:[1,0]
	v_sub_f32_e32 v160, v240, v160
	v_sub_f32_e32 v161, v241, v161
	v_sub_f32_e32 v162, v242, v162
	v_sub_f32_e32 v163, v243, v163
	s_waitcnt lgkmcnt(4)
	v_mfma_f32_16x16x32_bf16 v[180:183], v[216:219], v[136:139], v[180:183]
	ds_read_b128 v[236:239], v2 offset:30720
	v_pk_mul_f32 v[92:93], v[92:93], v[196:197] op_sel_hi:[1,0]
	v_pk_mul_f32 v[94:95], v[94:95], v[196:197] op_sel_hi:[1,0]
	v_lshlrev_b32_e32 v240, 16, v192
	v_and_b32_e32 v241, 0xffff0000, v192
	v_lshlrev_b32_e32 v242, 16, v193
	v_and_b32_e32 v243, 0xffff0000, v193
	v_cvt_pk_bf16_f32 v148, v156, v157
	v_cvt_pk_bf16_f32 v149, v158, v159
	v_cvt_pk_bf16_f32 v150, v160, v161
	v_cvt_pk_bf16_f32 v151, v162, v163
	s_waitcnt lgkmcnt(4)
	v_mfma_f32_16x16x32_bf16 v[184:187], v[220:223], v[136:139], v[184:187]
	ds_read_b128 v[212:215], v2 offset:19456
	v_pk_mul_f32 v[96:97], v[96:97], v[196:197] op_sel_hi:[1,0]
	v_pk_mul_f32 v[98:99], v[98:99], v[196:197] op_sel_hi:[1,0]
	v_sub_f32_e32 v164, v240, v164
	v_sub_f32_e32 v165, v241, v165
	v_sub_f32_e32 v166, v242, v166
	v_sub_f32_e32 v167, v243, v167
	s_waitcnt lgkmcnt(4)
	v_mfma_f32_16x16x32_bf16 v[172:175], v[224:227], v[140:143], v[172:175]
	ds_read_b128 v[216:219], v2 offset:23552
	v_lshlrev_b32_e32 v240, 16, v194
	v_and_b32_e32 v241, 0xffff0000, v194
	v_lshlrev_b32_e32 v242, 16, v195
	v_and_b32_e32 v243, 0xffff0000, v195
	s_waitcnt lgkmcnt(4)
	v_mfma_f32_16x16x32_bf16 v[176:179], v[228:231], v[140:143], v[176:179]
	ds_read_b128 v[220:223], v2 offset:27648
	v_sub_f32_e32 v168, v240, v168
	v_sub_f32_e32 v169, v241, v169
	v_sub_f32_e32 v170, v242, v170
	v_sub_f32_e32 v171, v243, v171
	s_waitcnt lgkmcnt(4)
	v_mfma_f32_16x16x32_bf16 v[180:183], v[232:235], v[140:143], v[180:183]
	ds_read_b128 v[224:227], v2 offset:31744
	v_cvt_pk_bf16_f32 v152, v164, v165
	v_cvt_pk_bf16_f32 v153, v166, v167
	v_cvt_pk_bf16_f32 v154, v168, v169
	v_cvt_pk_bf16_f32 v155, v170, v171
	s_waitcnt lgkmcnt(4)
	v_mfma_f32_16x16x32_bf16 v[184:187], v[236:239], v[140:143], v[184:187]
	s_waitcnt lgkmcnt(3)
	v_mfma_f32_16x16x32_bf16 v[172:175], v[212:215], v[144:147], v[172:175]
	s_waitcnt lgkmcnt(2)
	v_mfma_f32_16x16x32_bf16 v[176:179], v[216:219], v[144:147], v[176:179]
	s_waitcnt lgkmcnt(1)
	v_mfma_f32_16x16x32_bf16 v[180:183], v[220:223], v[144:147], v[180:183]
	s_waitcnt lgkmcnt(0)
	v_mfma_f32_16x16x32_bf16 v[184:187], v[224:227], v[144:147], v[184:187]
	s_waitcnt lgkmcnt(0)
	s_cmp_eq_u32 s6, 0
	s_cbranch_scc1 .Lsc_last2
	s_waitcnt vmcnt(0)
	s_barrier
	s_mov_b32 m0, s88
	s_nop 0
	global_load_lds_dwordx4 v[8:9], off
	s_add_i32 m0, s88, 0x400
	v_lshl_add_u64 v[30:31], v[8:9], 0, s[78:79]
	global_load_lds_dwordx4 v[30:31], off
	s_add_i32 m0, s88, 0x800
	v_lshl_add_u64 v[30:31], v[8:9], 0, s[98:99]
	global_load_lds_dwordx4 v[30:31], off
	s_add_i32 m0, s88, 0xc00
	v_lshl_add_u64 v[30:31], v[8:9], 0, s[100:101]
	global_load_lds_dwordx4 v[30:31], off
	s_mov_b32 m0, s92
	s_nop 0
	global_load_lds_dwordx4 v[20:21], off
	s_add_i32 m0, s92, 0x400
	v_lshl_add_u64 v[30:31], v[20:21], 0, s[78:79]
	global_load_lds_dwordx4 v[30:31], off
	s_mov_b32 m0, s89
	s_nop 0
	global_load_lds_dwordx4 v[10:11], off
	s_add_i32 m0, s89, 0x400
	v_lshl_add_u64 v[30:31], v[10:11], 0, s[78:79]
	global_load_lds_dwordx4 v[30:31], off
	s_add_i32 m0, s89, 0x800
	v_lshl_add_u64 v[30:31], v[10:11], 0, s[98:99]
	global_load_lds_dwordx4 v[30:31], off
	s_add_i32 m0, s89, 0xc00
	v_lshl_add_u64 v[30:31], v[10:11], 0, s[100:101]
	global_load_lds_dwordx4 v[30:31], off
	s_branch .Lsc_p3
